# tile loop headers: dropped the compiler's vmcnt(0) amid the accumulator clears in 7 GEMM instances (K loop's counted waits already cover the DMAs)
# speedup vs baseline: 1.0112x; 1.0057x over previous
; template <class Epi, class Sched, bool ALIGN_EPI = false, bool SP2 = false>
; __device__ __forceinline__ void gemm_phase(PG8_LAS unsigned char* lds, const Gemm g, const Sched& S, const Epi& E) {
;     ...
;         const bool has_next = S.next(ui + 1, nxt);
;         const char* nA = has_next ? (const char*)g.A + (size_t)nxt.pm * tstep : cA; const char* nB = has_next ? (const char*)g.Bt + (size_t)nxt.pn * tstep : cB;
;         for (int t = 0; t < nt; t += 2) {
;             const bool last = (t == nt - 2);
;             const char* a1 = cA + (size_t)(t + 1) * kstep;
;             const char* a2 = last ? nA : cA + (size_t)(t + 2) * kstep; const char* b2 = last ? nB : cB + (size_t)(t + 2) * kstep;
;     ...
; #pragma unroll
;         for (int a = 0; a < 2; ++a)
; #pragma unroll
;             for (int b = 0; b < 2; ++b)
; #pragma unroll
;                 for (int m = 0; m < 4; ++m)
; #pragma unroll
;                     for (int n = 0; n < 2; ++n) acc[a][b][m][n] = (f32x4){0.f, 0.f, 0.f, 0.f};
;         cur = nxt; cA = nA; cB = nB; ++ui;
.LBB0_558:
	s_ashr_i32 s17, s16, 31
	s_lshl_b64 s[18:19], s[16:17], 18
	s_mov_b64 s[4:5], s[46:47]
	s_add_u32 s18, s4, s18
	s_addc_u32 s19, s5, s19
	s_and_b64 s[22:23], s[6:7], exec
	s_cselect_b32 s17, s19, s55
	s_cselect_b32 s29, s18, s54
	s_ashr_i32 s15, s14, 31
	s_lshl_b64 s[22:23], s[14:15], 18
	s_add_u32 s24, s26, s22
	s_addc_u32 s25, s74, s23
	s_and_b64 s[22:23], s[6:7], exec
	s_cselect_b32 s15, s25, s1
	s_cselect_b32 vcc_lo, s24, s0
	s_add_u32 s54, s54, 0x20080
	s_addc_u32 s55, s55, 0
	s_add_u32 s22, s0, 0x100
	v_mov_b32_e32 v20, 0
	s_addc_u32 s23, s1, 0
	s_mov_b32 s35, -2
	v_mov_b32_e32 v21, v20
	v_mov_b32_e32 v22, v20
	v_mov_b32_e32 v23, v20
	v_mov_b32_e32 v24, v20
	v_mov_b32_e32 v25, v20
	v_mov_b32_e32 v26, v20
	v_mov_b32_e32 v27, v20
	v_mov_b32_e32 v36, v20
	v_mov_b32_e32 v37, v20
	v_mov_b32_e32 v38, v20
	v_mov_b32_e32 v39, v20
	v_mov_b32_e32 v40, v20
	v_mov_b32_e32 v41, v20
	v_mov_b32_e32 v42, v20
	v_mov_b32_e32 v43, v20
	v_mov_b32_e32 v52, v20
	v_mov_b32_e32 v53, v20
	v_mov_b32_e32 v54, v20
	v_mov_b32_e32 v55, v20
	v_mov_b32_e32 v56, v20
	v_mov_b32_e32 v57, v20
	v_mov_b32_e32 v58, v20
	v_mov_b32_e32 v59, v20
	v_mov_b32_e32 v68, v20
	v_mov_b32_e32 v69, v20
	v_mov_b32_e32 v70, v20
	v_mov_b32_e32 v71, v20
	v_mov_b32_e32 v72, v20
	v_mov_b32_e32 v73, v20
	v_mov_b32_e32 v74, v20
	v_mov_b32_e32 v75, v20
	v_mov_b32_e32 v28, v20
	v_mov_b32_e32 v29, v20
	v_mov_b32_e32 v30, v20
	v_mov_b32_e32 v31, v20
	v_mov_b32_e32 v32, v20
	v_mov_b32_e32 v33, v20
	v_mov_b32_e32 v34, v20
	v_mov_b32_e32 v35, v20
	v_mov_b32_e32 v44, v20
	v_mov_b32_e32 v45, v20
	v_mov_b32_e32 v46, v20
	v_mov_b32_e32 v47, v20
	v_mov_b32_e32 v48, v20
	v_mov_b32_e32 v49, v20
	v_mov_b32_e32 v50, v20
	v_mov_b32_e32 v51, v20
	v_mov_b32_e32 v60, v20
	v_mov_b32_e32 v61, v20
	v_mov_b32_e32 v62, v20
	v_mov_b32_e32 v63, v20
	v_mov_b32_e32 v64, v20
	v_mov_b32_e32 v65, v20
	v_mov_b32_e32 v66, v20
	v_mov_b32_e32 v67, v20
	v_mov_b32_e32 v76, v20
	v_mov_b32_e32 v77, v20
	v_mov_b32_e32 v78, v20
	v_mov_b32_e32 v79, v20
	v_mov_b32_e32 v80, v20
	v_mov_b32_e32 v81, v20
	v_mov_b32_e32 v82, v20
	v_mov_b32_e32 v83, v20
	v_mov_b32_e32 v84, v20
	v_mov_b32_e32 v85, v20
	v_mov_b32_e32 v86, v20
	v_mov_b32_e32 v87, v20
	v_mov_b32_e32 v88, v20
	v_mov_b32_e32 v89, v20
	v_mov_b32_e32 v90, v20
	v_mov_b32_e32 v91, v20
	v_mov_b32_e32 v116, v20
	v_mov_b32_e32 v117, v20
	v_mov_b32_e32 v118, v20
	v_mov_b32_e32 v119, v20
	v_mov_b32_e32 v120, v20
	v_mov_b32_e32 v121, v20
	v_mov_b32_e32 v122, v20
	v_mov_b32_e32 v123, v20
	v_mov_b32_e32 v132, v20
	v_mov_b32_e32 v133, v20
	v_mov_b32_e32 v134, v20
	v_mov_b32_e32 v135, v20
	v_mov_b32_e32 v136, v20
	v_mov_b32_e32 v137, v20
	v_mov_b32_e32 v138, v20
	v_mov_b32_e32 v139, v20
	v_mov_b32_e32 v148, v20
	v_mov_b32_e32 v149, v20
	v_mov_b32_e32 v150, v20
	v_mov_b32_e32 v151, v20
	v_mov_b32_e32 v152, v20
	v_mov_b32_e32 v153, v20
	v_mov_b32_e32 v154, v20
	v_mov_b32_e32 v155, v20
	v_mov_b32_e32 v100, v20
	v_mov_b32_e32 v101, v20
	v_mov_b32_e32 v102, v20
	v_mov_b32_e32 v103, v20
	v_mov_b32_e32 v104, v20
	v_mov_b32_e32 v105, v20
	v_mov_b32_e32 v106, v20
	v_mov_b32_e32 v107, v20
	v_mov_b32_e32 v124, v20
	v_mov_b32_e32 v125, v20
	v_mov_b32_e32 v126, v20
	v_mov_b32_e32 v127, v20
	v_mov_b32_e32 v128, v20
	v_mov_b32_e32 v129, v20
	v_mov_b32_e32 v130, v20
	v_mov_b32_e32 v131, v20
	v_mov_b32_e32 v140, v20
	v_mov_b32_e32 v141, v20
	v_mov_b32_e32 v142, v20
	v_mov_b32_e32 v143, v20
	v_mov_b32_e32 v144, v20
	v_mov_b32_e32 v145, v20
	v_mov_b32_e32 v146, v20
	v_mov_b32_e32 v147, v20
	v_mov_b32_e32 v156, v20
	v_mov_b32_e32 v157, v20
	v_mov_b32_e32 v158, v20
	v_mov_b32_e32 v159, v20
	v_mov_b32_e32 v160, v20
	v_mov_b32_e32 v161, v20
	v_mov_b32_e32 v162, v20
	v_mov_b32_e32 v163, v20

; template <class Epi, class Sched, bool ALIGN_EPI = false, bool SP2 = false>
; __device__ __forceinline__ void gemm_phase(PG8_LAS unsigned char* lds, const Gemm g, const Sched& S, const Epi& E) {
;     ...
;         const bool has_next = S.next(ui + 1, nxt);
;         const char* nA = has_next ? (const char*)g.A + (size_t)nxt.pm * tstep : cA; const char* nB = has_next ? (const char*)g.Bt + (size_t)nxt.pn * tstep : cB;
;         for (int t = 0; t < nt; t += 2) {
;             const bool last = (t == nt - 2);
;             const char* a1 = cA + (size_t)(t + 1) * kstep;
;             const char* a2 = last ? nA : cA + (size_t)(t + 2) * kstep; const char* b2 = last ? nB : cB + (size_t)(t + 2) * kstep;
;     ...
; #pragma unroll
;         for (int a = 0; a < 2; ++a)
; #pragma unroll
;             for (int b = 0; b < 2; ++b)
; #pragma unroll
;                 for (int m = 0; m < 4; ++m)
; #pragma unroll
;                     for (int n = 0; n < 2; ++n) acc[a][b][m][n] = (f32x4){0.f, 0.f, 0.f, 0.f};
;         cur = nxt; cA = nA; cB = nB; ++ui;
.LBB0_580:
	s_ashr_i32 s73, s72, 31
	s_lshl_b64 s[22:23], s[72:73], 19
	s_add_u32 s24, s30, s22
	s_addc_u32 s25, s31, s23
	s_and_b64 s[22:23], s[14:15], exec
	s_cselect_b32 s29, s25, s1
	s_cselect_b32 s73, s24, s0
	s_ashr_i32 s17, s16, 31
	s_lshl_b64 s[22:23], s[16:17], 19
	s_add_u32 s54, s6, s22
	s_addc_u32 s55, s7, s23
	s_and_b64 s[22:23], s[14:15], exec
	s_cselect_b32 s17, s55, s67
	s_cselect_b32 s22, s54, s66
	s_add_u32 vcc_lo, s0, 0x40080
	s_addc_u32 vcc_hi, s1, 0
	s_add_u32 s23, s66, 0x100
	v_mov_b32_e32 v24, 0
	s_addc_u32 s35, s67, 0
	s_mov_b32 s60, -2
	v_mov_b32_e32 v25, v24
	v_mov_b32_e32 v26, v24
	v_mov_b32_e32 v27, v24
	v_mov_b32_e32 v20, v24
	v_mov_b32_e32 v21, v24
	v_mov_b32_e32 v22, v24
	v_mov_b32_e32 v23, v24
	v_mov_b32_e32 v40, v24
	v_mov_b32_e32 v41, v24
	v_mov_b32_e32 v42, v24
	v_mov_b32_e32 v43, v24
	v_mov_b32_e32 v36, v24
	v_mov_b32_e32 v37, v24
	v_mov_b32_e32 v38, v24
	v_mov_b32_e32 v39, v24
	v_mov_b32_e32 v56, v24
	v_mov_b32_e32 v57, v24
	v_mov_b32_e32 v58, v24
	v_mov_b32_e32 v59, v24
	v_mov_b32_e32 v52, v24
	v_mov_b32_e32 v53, v24
	v_mov_b32_e32 v54, v24
	v_mov_b32_e32 v55, v24
	v_mov_b32_e32 v72, v24
	v_mov_b32_e32 v73, v24
	v_mov_b32_e32 v74, v24
	v_mov_b32_e32 v75, v24
	v_mov_b32_e32 v68, v24
	v_mov_b32_e32 v69, v24
	v_mov_b32_e32 v70, v24
	v_mov_b32_e32 v71, v24
	v_mov_b32_e32 v32, v24
	v_mov_b32_e32 v33, v24
	v_mov_b32_e32 v34, v24
	v_mov_b32_e32 v35, v24
	v_mov_b32_e32 v28, v24
	v_mov_b32_e32 v29, v24
	v_mov_b32_e32 v30, v24
	v_mov_b32_e32 v31, v24
	v_mov_b32_e32 v48, v24
	v_mov_b32_e32 v49, v24
	v_mov_b32_e32 v50, v24
	v_mov_b32_e32 v51, v24
	v_mov_b32_e32 v44, v24
	v_mov_b32_e32 v45, v24
	v_mov_b32_e32 v46, v24
	v_mov_b32_e32 v47, v24
	v_mov_b32_e32 v64, v24
	v_mov_b32_e32 v65, v24
	v_mov_b32_e32 v66, v24
	v_mov_b32_e32 v67, v24
	v_mov_b32_e32 v60, v24
	v_mov_b32_e32 v61, v24
	v_mov_b32_e32 v62, v24
	v_mov_b32_e32 v63, v24
	v_mov_b32_e32 v80, v24
	v_mov_b32_e32 v81, v24
	v_mov_b32_e32 v82, v24
	v_mov_b32_e32 v83, v24
	v_mov_b32_e32 v76, v24
	v_mov_b32_e32 v77, v24
	v_mov_b32_e32 v78, v24
	v_mov_b32_e32 v79, v24
	v_mov_b32_e32 v88, v24
	v_mov_b32_e32 v89, v24
	v_mov_b32_e32 v90, v24
	v_mov_b32_e32 v91, v24
	v_mov_b32_e32 v84, v24
	v_mov_b32_e32 v85, v24
	v_mov_b32_e32 v86, v24
	v_mov_b32_e32 v87, v24
	v_mov_b32_e32 v104, v24
	v_mov_b32_e32 v105, v24
	v_mov_b32_e32 v106, v24
	v_mov_b32_e32 v107, v24
	v_mov_b32_e32 v100, v24
	v_mov_b32_e32 v101, v24
	v_mov_b32_e32 v102, v24
	v_mov_b32_e32 v103, v24
	v_mov_b32_e32 v136, v24
	v_mov_b32_e32 v137, v24
	v_mov_b32_e32 v138, v24
	v_mov_b32_e32 v139, v24
	v_mov_b32_e32 v128, v24
	v_mov_b32_e32 v129, v24
	v_mov_b32_e32 v130, v24
	v_mov_b32_e32 v131, v24
	v_mov_b32_e32 v152, v24
	v_mov_b32_e32 v153, v24
	v_mov_b32_e32 v154, v24
	v_mov_b32_e32 v155, v24
	v_mov_b32_e32 v148, v24
	v_mov_b32_e32 v149, v24
	v_mov_b32_e32 v150, v24
	v_mov_b32_e32 v151, v24
	v_mov_b32_e32 v96, v24
	v_mov_b32_e32 v97, v24
	v_mov_b32_e32 v98, v24
	v_mov_b32_e32 v99, v24
	v_mov_b32_e32 v92, v24
	v_mov_b32_e32 v93, v24
	v_mov_b32_e32 v94, v24
	v_mov_b32_e32 v95, v24
	v_mov_b32_e32 v120, v24
	v_mov_b32_e32 v121, v24
	v_mov_b32_e32 v122, v24
	v_mov_b32_e32 v123, v24
	v_mov_b32_e32 v116, v24
	v_mov_b32_e32 v117, v24
	v_mov_b32_e32 v118, v24
	v_mov_b32_e32 v119, v24
	v_mov_b32_e32 v144, v24
	v_mov_b32_e32 v145, v24
	v_mov_b32_e32 v146, v24
	v_mov_b32_e32 v147, v24
	v_mov_b32_e32 v140, v24
	v_mov_b32_e32 v141, v24
	v_mov_b32_e32 v142, v24
	v_mov_b32_e32 v143, v24
	v_mov_b32_e32 v160, v24
	v_mov_b32_e32 v161, v24
	v_mov_b32_e32 v162, v24
	v_mov_b32_e32 v163, v24
	v_mov_b32_e32 v156, v24
	v_mov_b32_e32 v157, v24
	v_mov_b32_e32 v158, v24
	v_mov_b32_e32 v159, v24

; template <class Epi, class Sched, bool ALIGN_EPI = false, bool SP2 = false>
; __device__ __forceinline__ void gemm_phase(PG8_LAS unsigned char* lds, const Gemm g, const Sched& S, const Epi& E) {
;     ...
;         const bool has_next = S.next(ui + 1, nxt);
;         const char* nA = has_next ? (const char*)g.A + (size_t)nxt.pm * tstep : cA; const char* nB = has_next ? (const char*)g.Bt + (size_t)nxt.pn * tstep : cB;
;         for (int t = 0; t < nt; t += 2) {
;             const bool last = (t == nt - 2);
;             const char* a1 = cA + (size_t)(t + 1) * kstep;
;             const char* a2 = last ? nA : cA + (size_t)(t + 2) * kstep; const char* b2 = last ? nB : cB + (size_t)(t + 2) * kstep;
;     ...
; #pragma unroll
;         for (int a = 0; a < 2; ++a)
; #pragma unroll
;             for (int b = 0; b < 2; ++b)
; #pragma unroll
;                 for (int m = 0; m < 4; ++m)
; #pragma unroll
;                     for (int n = 0; n < 2; ++n) acc[a][b][m][n] = (f32x4){0.f, 0.f, 0.f, 0.f};
;         cur = nxt; cA = nA; cB = nB; ++ui;
.LBB0_675:
	s_ashr_i32 s13, s12, 31
	s_lshl_b64 s[14:15], s[12:13], 18
	s_add_u32 s14, s36, s14
	s_addc_u32 s15, s37, s15
	s_and_b64 s[16:17], s[6:7], exec
	s_cselect_b32 s13, s15, s19
	s_cselect_b32 s67, s14, s18
	s_ashr_i32 s11, s10, 31
	s_lshl_b64 s[16:17], s[10:11], 18
	s_add_u32 s16, s26, s16
	s_addc_u32 s17, s54, s17
	s_and_b64 s[22:23], s[6:7], exec
	s_cselect_b32 s11, s17, s1
	s_cselect_b32 s22, s16, s0
	s_add_u32 s18, s18, 0x20080
	s_addc_u32 s19, s19, 0
	s_add_u32 s23, s0, 0x100
	v_mov_b32_e32 v20, 0
	s_addc_u32 s35, s1, 0
	s_mov_b32 s60, -2
	v_mov_b32_e32 v21, v20
	v_mov_b32_e32 v22, v20
	v_mov_b32_e32 v23, v20
	v_mov_b32_e32 v24, v20
	v_mov_b32_e32 v25, v20
	v_mov_b32_e32 v26, v20
	v_mov_b32_e32 v27, v20
	v_mov_b32_e32 v32, v20
	v_mov_b32_e32 v33, v20
	v_mov_b32_e32 v34, v20
	v_mov_b32_e32 v35, v20
	v_mov_b32_e32 v40, v20
	v_mov_b32_e32 v41, v20
	v_mov_b32_e32 v42, v20
	v_mov_b32_e32 v43, v20
	v_mov_b32_e32 v48, v20
	v_mov_b32_e32 v49, v20
	v_mov_b32_e32 v50, v20
	v_mov_b32_e32 v51, v20
	v_mov_b32_e32 v56, v20
	v_mov_b32_e32 v57, v20
	v_mov_b32_e32 v58, v20
	v_mov_b32_e32 v59, v20
	v_mov_b32_e32 v64, v20
	v_mov_b32_e32 v65, v20
	v_mov_b32_e32 v66, v20
	v_mov_b32_e32 v67, v20
	v_mov_b32_e32 v72, v20
	v_mov_b32_e32 v73, v20
	v_mov_b32_e32 v74, v20
	v_mov_b32_e32 v75, v20
	v_mov_b32_e32 v28, v20
	v_mov_b32_e32 v29, v20
	v_mov_b32_e32 v30, v20
	v_mov_b32_e32 v31, v20
	v_mov_b32_e32 v36, v20
	v_mov_b32_e32 v37, v20
	v_mov_b32_e32 v38, v20
	v_mov_b32_e32 v39, v20
	v_mov_b32_e32 v44, v20
	v_mov_b32_e32 v45, v20
	v_mov_b32_e32 v46, v20
	v_mov_b32_e32 v47, v20
	v_mov_b32_e32 v52, v20
	v_mov_b32_e32 v53, v20
	v_mov_b32_e32 v54, v20
	v_mov_b32_e32 v55, v20
	v_mov_b32_e32 v60, v20
	v_mov_b32_e32 v61, v20
	v_mov_b32_e32 v62, v20
	v_mov_b32_e32 v63, v20
	v_mov_b32_e32 v68, v20
	v_mov_b32_e32 v69, v20
	v_mov_b32_e32 v70, v20
	v_mov_b32_e32 v71, v20
	v_mov_b32_e32 v76, v20
	v_mov_b32_e32 v77, v20
	v_mov_b32_e32 v78, v20
	v_mov_b32_e32 v79, v20
	v_mov_b32_e32 v80, v20
	v_mov_b32_e32 v81, v20
	v_mov_b32_e32 v82, v20
	v_mov_b32_e32 v83, v20
	v_mov_b32_e32 v84, v20
	v_mov_b32_e32 v85, v20
	v_mov_b32_e32 v86, v20
	v_mov_b32_e32 v87, v20
	v_mov_b32_e32 v88, v20
	v_mov_b32_e32 v89, v20
	v_mov_b32_e32 v90, v20
	v_mov_b32_e32 v91, v20
	v_mov_b32_e32 v96, v20
	v_mov_b32_e32 v97, v20
	v_mov_b32_e32 v98, v20
	v_mov_b32_e32 v99, v20
	v_mov_b32_e32 v104, v20
	v_mov_b32_e32 v105, v20
	v_mov_b32_e32 v106, v20
	v_mov_b32_e32 v107, v20
	v_mov_b32_e32 v112, v20
	v_mov_b32_e32 v113, v20
	v_mov_b32_e32 v114, v20
	v_mov_b32_e32 v115, v20
	v_mov_b32_e32 v120, v20
	v_mov_b32_e32 v121, v20
	v_mov_b32_e32 v122, v20
	v_mov_b32_e32 v123, v20
	v_mov_b32_e32 v128, v20
	v_mov_b32_e32 v129, v20
	v_mov_b32_e32 v130, v20
	v_mov_b32_e32 v131, v20
	v_mov_b32_e32 v136, v20
	v_mov_b32_e32 v137, v20
	v_mov_b32_e32 v138, v20
	v_mov_b32_e32 v139, v20
	v_mov_b32_e32 v92, v20
	v_mov_b32_e32 v93, v20
	v_mov_b32_e32 v94, v20
	v_mov_b32_e32 v95, v20
	v_mov_b32_e32 v100, v20
	v_mov_b32_e32 v101, v20
	v_mov_b32_e32 v102, v20
	v_mov_b32_e32 v103, v20
	v_mov_b32_e32 v108, v20
	v_mov_b32_e32 v109, v20
	v_mov_b32_e32 v110, v20
	v_mov_b32_e32 v111, v20
	v_mov_b32_e32 v116, v20
	v_mov_b32_e32 v117, v20
	v_mov_b32_e32 v118, v20
	v_mov_b32_e32 v119, v20
	v_mov_b32_e32 v124, v20
	v_mov_b32_e32 v125, v20
	v_mov_b32_e32 v126, v20
	v_mov_b32_e32 v127, v20
	v_mov_b32_e32 v132, v20
	v_mov_b32_e32 v133, v20
	v_mov_b32_e32 v134, v20
	v_mov_b32_e32 v135, v20
	v_mov_b32_e32 v140, v20
	v_mov_b32_e32 v141, v20
	v_mov_b32_e32 v142, v20
	v_mov_b32_e32 v143, v20
	v_mov_b32_e32 v144, v20
	v_mov_b32_e32 v145, v20
	v_mov_b32_e32 v146, v20
	v_mov_b32_e32 v147, v20

; template <class Epi, class Sched, bool ALIGN_EPI = false, bool SP2 = false>
; __device__ __forceinline__ void gemm_phase(PG8_LAS unsigned char* lds, const Gemm g, const Sched& S, const Epi& E) {
;     ...
;         const bool has_next = S.next(ui + 1, nxt);
;         const char* nA = has_next ? (const char*)g.A + (size_t)nxt.pm * tstep : cA; const char* nB = has_next ? (const char*)g.Bt + (size_t)nxt.pn * tstep : cB;
;         for (int t = 0; t < nt; t += 2) {
;             const bool last = (t == nt - 2);
;             const char* a1 = cA + (size_t)(t + 1) * kstep;
;             const char* a2 = last ? nA : cA + (size_t)(t + 2) * kstep; const char* b2 = last ? nB : cB + (size_t)(t + 2) * kstep;
;     ...
; #pragma unroll
;         for (int a = 0; a < 2; ++a)
; #pragma unroll
;             for (int b = 0; b < 2; ++b)
; #pragma unroll
;                 for (int m = 0; m < 4; ++m)
; #pragma unroll
;                     for (int n = 0; n < 2; ++n) acc[a][b][m][n] = (f32x4){0.f, 0.f, 0.f, 0.f};
;         cur = nxt; cA = nA; cB = nB; ++ui;
.LBB0_698:
	s_ashr_i32 s13, s12, 31
	s_lshl_b64 s[14:15], s[12:13], 18
	s_add_u32 s14, s50, s14
	s_addc_u32 s15, s51, s15
	s_and_b64 s[16:17], s[8:9], exec
	s_cselect_b32 s13, s15, s19
	s_cselect_b32 s67, s14, s18
	s_ashr_i32 s11, s10, 31
	s_lshl_b64 s[16:17], s[10:11], 18
	s_add_u32 s16, s26, s16
	s_addc_u32 s17, s54, s17
	s_and_b64 s[22:23], s[8:9], exec
	s_cselect_b32 s11, s17, s1
	s_cselect_b32 s22, s16, s0
	s_add_u32 s18, s18, 0x20080
	s_addc_u32 s19, s19, 0
	s_add_u32 s23, s0, 0x100
	v_mov_b32_e32 v20, 0
	s_addc_u32 s35, s1, 0
	s_mov_b32 s60, -2
	v_mov_b32_e32 v21, v20
	v_mov_b32_e32 v22, v20
	v_mov_b32_e32 v23, v20
	v_mov_b32_e32 v24, v20
	v_mov_b32_e32 v25, v20
	v_mov_b32_e32 v26, v20
	v_mov_b32_e32 v27, v20
	v_mov_b32_e32 v36, v20
	v_mov_b32_e32 v37, v20
	v_mov_b32_e32 v38, v20
	v_mov_b32_e32 v39, v20
	v_mov_b32_e32 v40, v20
	v_mov_b32_e32 v41, v20
	v_mov_b32_e32 v42, v20
	v_mov_b32_e32 v43, v20
	v_mov_b32_e32 v52, v20
	v_mov_b32_e32 v53, v20
	v_mov_b32_e32 v54, v20
	v_mov_b32_e32 v55, v20
	v_mov_b32_e32 v56, v20
	v_mov_b32_e32 v57, v20
	v_mov_b32_e32 v58, v20
	v_mov_b32_e32 v59, v20
	v_mov_b32_e32 v68, v20
	v_mov_b32_e32 v69, v20
	v_mov_b32_e32 v70, v20
	v_mov_b32_e32 v71, v20
	v_mov_b32_e32 v72, v20
	v_mov_b32_e32 v73, v20
	v_mov_b32_e32 v74, v20
	v_mov_b32_e32 v75, v20
	v_mov_b32_e32 v28, v20
	v_mov_b32_e32 v29, v20
	v_mov_b32_e32 v30, v20
	v_mov_b32_e32 v31, v20
	v_mov_b32_e32 v32, v20
	v_mov_b32_e32 v33, v20
	v_mov_b32_e32 v34, v20
	v_mov_b32_e32 v35, v20
	v_mov_b32_e32 v44, v20
	v_mov_b32_e32 v45, v20
	v_mov_b32_e32 v46, v20
	v_mov_b32_e32 v47, v20
	v_mov_b32_e32 v48, v20
	v_mov_b32_e32 v49, v20
	v_mov_b32_e32 v50, v20
	v_mov_b32_e32 v51, v20
	v_mov_b32_e32 v60, v20
	v_mov_b32_e32 v61, v20
	v_mov_b32_e32 v62, v20
	v_mov_b32_e32 v63, v20
	v_mov_b32_e32 v64, v20
	v_mov_b32_e32 v65, v20
	v_mov_b32_e32 v66, v20
	v_mov_b32_e32 v67, v20
	v_mov_b32_e32 v76, v20
	v_mov_b32_e32 v77, v20
	v_mov_b32_e32 v78, v20
	v_mov_b32_e32 v79, v20
	v_mov_b32_e32 v80, v20
	v_mov_b32_e32 v81, v20
	v_mov_b32_e32 v82, v20
	v_mov_b32_e32 v83, v20
	v_mov_b32_e32 v84, v20
	v_mov_b32_e32 v85, v20
	v_mov_b32_e32 v86, v20
	v_mov_b32_e32 v87, v20
	v_mov_b32_e32 v88, v20
	v_mov_b32_e32 v89, v20
	v_mov_b32_e32 v90, v20
	v_mov_b32_e32 v91, v20
	v_mov_b32_e32 v100, v20
	v_mov_b32_e32 v101, v20
	v_mov_b32_e32 v102, v20
	v_mov_b32_e32 v103, v20
	v_mov_b32_e32 v104, v20
	v_mov_b32_e32 v105, v20
	v_mov_b32_e32 v106, v20
	v_mov_b32_e32 v107, v20
	v_mov_b32_e32 v116, v20
	v_mov_b32_e32 v117, v20
	v_mov_b32_e32 v118, v20
	v_mov_b32_e32 v119, v20
	v_mov_b32_e32 v120, v20
	v_mov_b32_e32 v121, v20
	v_mov_b32_e32 v122, v20
	v_mov_b32_e32 v123, v20
	v_mov_b32_e32 v132, v20
	v_mov_b32_e32 v133, v20
	v_mov_b32_e32 v134, v20
	v_mov_b32_e32 v135, v20
	v_mov_b32_e32 v136, v20
	v_mov_b32_e32 v137, v20
	v_mov_b32_e32 v138, v20
	v_mov_b32_e32 v139, v20
	v_mov_b32_e32 v92, v20
	v_mov_b32_e32 v93, v20
	v_mov_b32_e32 v94, v20
	v_mov_b32_e32 v95, v20
	v_mov_b32_e32 v96, v20
	v_mov_b32_e32 v97, v20
	v_mov_b32_e32 v98, v20
	v_mov_b32_e32 v99, v20
	v_mov_b32_e32 v108, v20
	v_mov_b32_e32 v109, v20
	v_mov_b32_e32 v110, v20
	v_mov_b32_e32 v111, v20
	v_mov_b32_e32 v112, v20
	v_mov_b32_e32 v113, v20
	v_mov_b32_e32 v114, v20
	v_mov_b32_e32 v115, v20
	v_mov_b32_e32 v124, v20
	v_mov_b32_e32 v125, v20
	v_mov_b32_e32 v126, v20
	v_mov_b32_e32 v127, v20
	v_mov_b32_e32 v128, v20
	v_mov_b32_e32 v129, v20
	v_mov_b32_e32 v130, v20
	v_mov_b32_e32 v131, v20
	v_mov_b32_e32 v140, v20
	v_mov_b32_e32 v141, v20
	v_mov_b32_e32 v142, v20
	v_mov_b32_e32 v143, v20
	v_mov_b32_e32 v144, v20
	v_mov_b32_e32 v145, v20
	v_mov_b32_e32 v146, v20
	v_mov_b32_e32 v147, v20

; template <class Epi, class Sched, bool ALIGN_EPI = false, bool SP2 = false>
; __device__ __forceinline__ void gemm_phase(PG8_LAS unsigned char* lds, const Gemm g, const Sched& S, const Epi& E) {
;     ...
;         const bool has_next = S.next(ui + 1, nxt);
;         const char* nA = has_next ? (const char*)g.A + (size_t)nxt.pm * tstep : cA; const char* nB = has_next ? (const char*)g.Bt + (size_t)nxt.pn * tstep : cB;
;         for (int t = 0; t < nt; t += 2) {
;             const bool last = (t == nt - 2);
;             const char* a1 = cA + (size_t)(t + 1) * kstep;
;             const char* a2 = last ? nA : cA + (size_t)(t + 2) * kstep; const char* b2 = last ? nB : cB + (size_t)(t + 2) * kstep;
;     ...
; #pragma unroll
;         for (int a = 0; a < 2; ++a)
; #pragma unroll
;             for (int b = 0; b < 2; ++b)
; #pragma unroll
;                 for (int m = 0; m < 4; ++m)
; #pragma unroll
;                     for (int n = 0; n < 2; ++n) acc[a][b][m][n] = (f32x4){0.f, 0.f, 0.f, 0.f};
;         cur = nxt; cA = nA; cB = nB; ++ui;
.LBB0_773:
	s_ashr_i32 s17, s16, 31
	s_lshl_b64 s[18:19], s[16:17], 19
	s_add_u32 s18, s68, s18
	s_addc_u32 s19, s69, s19
	s_and_b64 s[22:23], s[10:11], exec
	s_cselect_b32 s17, s19, s55
	s_cselect_b32 s75, s18, s54
	s_ashr_i32 s15, s14, 31
	s_lshl_b64 s[22:23], s[14:15], 19
	s_add_u32 s24, s26, s22
	s_addc_u32 s25, s58, s23
	s_and_b64 s[22:23], s[10:11], exec
	s_cselect_b32 s15, s25, s1
	s_cselect_b32 s22, s24, s0
	s_add_u32 s54, s54, 0x40080
	s_addc_u32 s55, s55, 0
	s_add_u32 s23, s0, 0x100
	v_mov_b32_e32 v20, 0
	s_addc_u32 s35, s1, 0
	s_mov_b32 s60, -2
	s_waitcnt lgkmcnt(0)
	v_mov_b32_e32 v21, v20
	v_mov_b32_e32 v22, v20
	v_mov_b32_e32 v23, v20
	v_mov_b32_e32 v24, v20
	v_mov_b32_e32 v25, v20
	v_mov_b32_e32 v26, v20
	v_mov_b32_e32 v27, v20
	v_mov_b32_e32 v36, v20
	v_mov_b32_e32 v37, v20
	v_mov_b32_e32 v38, v20
	v_mov_b32_e32 v39, v20
	v_mov_b32_e32 v40, v20
	v_mov_b32_e32 v41, v20
	v_mov_b32_e32 v42, v20
	v_mov_b32_e32 v43, v20
	v_mov_b32_e32 v52, v20
	v_mov_b32_e32 v53, v20
	v_mov_b32_e32 v54, v20
	v_mov_b32_e32 v55, v20
	v_mov_b32_e32 v56, v20
	v_mov_b32_e32 v57, v20
	v_mov_b32_e32 v58, v20
	v_mov_b32_e32 v59, v20
	v_mov_b32_e32 v68, v20
	v_mov_b32_e32 v69, v20
	v_mov_b32_e32 v70, v20
	v_mov_b32_e32 v71, v20
	v_mov_b32_e32 v72, v20
	v_mov_b32_e32 v73, v20
	v_mov_b32_e32 v74, v20
	v_mov_b32_e32 v75, v20
	v_mov_b32_e32 v28, v20
	v_mov_b32_e32 v29, v20
	v_mov_b32_e32 v30, v20
	v_mov_b32_e32 v31, v20
	v_mov_b32_e32 v32, v20
	v_mov_b32_e32 v33, v20
	v_mov_b32_e32 v34, v20
	v_mov_b32_e32 v35, v20
	v_mov_b32_e32 v44, v20
	v_mov_b32_e32 v45, v20
	v_mov_b32_e32 v46, v20
	v_mov_b32_e32 v47, v20
	v_mov_b32_e32 v48, v20
	v_mov_b32_e32 v49, v20
	v_mov_b32_e32 v50, v20
	v_mov_b32_e32 v51, v20
	v_mov_b32_e32 v60, v20
	v_mov_b32_e32 v61, v20
	v_mov_b32_e32 v62, v20
	v_mov_b32_e32 v63, v20
	v_mov_b32_e32 v64, v20
	v_mov_b32_e32 v65, v20
	v_mov_b32_e32 v66, v20
	v_mov_b32_e32 v67, v20
	v_mov_b32_e32 v76, v20
	v_mov_b32_e32 v77, v20
	v_mov_b32_e32 v78, v20
	v_mov_b32_e32 v79, v20
	v_mov_b32_e32 v80, v20
	v_mov_b32_e32 v81, v20
	v_mov_b32_e32 v82, v20
	v_mov_b32_e32 v83, v20
	v_mov_b32_e32 v84, v20
	v_mov_b32_e32 v85, v20
	v_mov_b32_e32 v86, v20
	v_mov_b32_e32 v87, v20
	v_mov_b32_e32 v88, v20
	v_mov_b32_e32 v89, v20
	v_mov_b32_e32 v90, v20
	v_mov_b32_e32 v91, v20
	v_mov_b32_e32 v100, v20
	v_mov_b32_e32 v101, v20
	v_mov_b32_e32 v102, v20
	v_mov_b32_e32 v103, v20
	v_mov_b32_e32 v104, v20
	v_mov_b32_e32 v105, v20
	v_mov_b32_e32 v106, v20
	v_mov_b32_e32 v107, v20
	v_mov_b32_e32 v116, v20
	v_mov_b32_e32 v117, v20
	v_mov_b32_e32 v118, v20
	v_mov_b32_e32 v119, v20
	v_mov_b32_e32 v120, v20
	v_mov_b32_e32 v121, v20
	v_mov_b32_e32 v122, v20
	v_mov_b32_e32 v123, v20
	v_mov_b32_e32 v132, v20
	v_mov_b32_e32 v133, v20
	v_mov_b32_e32 v134, v20
	v_mov_b32_e32 v135, v20
	v_mov_b32_e32 v136, v20
	v_mov_b32_e32 v137, v20
	v_mov_b32_e32 v138, v20
	v_mov_b32_e32 v139, v20
	v_mov_b32_e32 v92, v20
	v_mov_b32_e32 v93, v20
	v_mov_b32_e32 v94, v20
	v_mov_b32_e32 v95, v20
	v_mov_b32_e32 v96, v20
	v_mov_b32_e32 v97, v20
	v_mov_b32_e32 v98, v20
	v_mov_b32_e32 v99, v20
	v_mov_b32_e32 v108, v20
	v_mov_b32_e32 v109, v20
	v_mov_b32_e32 v110, v20
	v_mov_b32_e32 v111, v20
	v_mov_b32_e32 v112, v20
	v_mov_b32_e32 v113, v20
	v_mov_b32_e32 v114, v20
	v_mov_b32_e32 v115, v20
	v_mov_b32_e32 v124, v20
	v_mov_b32_e32 v125, v20
	v_mov_b32_e32 v126, v20
	v_mov_b32_e32 v127, v20
	v_mov_b32_e32 v128, v20
	v_mov_b32_e32 v129, v20
	v_mov_b32_e32 v130, v20
	v_mov_b32_e32 v131, v20
	v_mov_b32_e32 v140, v20
	v_mov_b32_e32 v141, v20
	v_mov_b32_e32 v142, v20
	v_mov_b32_e32 v143, v20
	v_mov_b32_e32 v144, v20
	v_mov_b32_e32 v145, v20
	v_mov_b32_e32 v146, v20
	v_mov_b32_e32 v147, v20

; template <class Epi, class Sched, bool ALIGN_EPI = false, bool SP2 = false>
; __device__ __forceinline__ void gemm_phase(PG8_LAS unsigned char* lds, const Gemm g, const Sched& S, const Epi& E) {
;     ...
;         const bool has_next = S.next(ui + 1, nxt);
;         const char* nA = has_next ? (const char*)g.A + (size_t)nxt.pm * tstep : cA; const char* nB = has_next ? (const char*)g.Bt + (size_t)nxt.pn * tstep : cB;
;         for (int t = 0; t < nt; t += 2) {
;             const bool last = (t == nt - 2);
;             const char* a1 = cA + (size_t)(t + 1) * kstep;
;             const char* a2 = last ? nA : cA + (size_t)(t + 2) * kstep; const char* b2 = last ? nB : cB + (size_t)(t + 2) * kstep;
;     ...
; #pragma unroll
;         for (int a = 0; a < 2; ++a)
; #pragma unroll
;             for (int b = 0; b < 2; ++b)
; #pragma unroll
;                 for (int m = 0; m < 4; ++m)
; #pragma unroll
;                     for (int n = 0; n < 2; ++n) acc[a][b][m][n] = (f32x4){0.f, 0.f, 0.f, 0.f};
;         cur = nxt; cA = nA; cB = nB; ++ui;
.LBB0_866:
	s_ashr_i32 s15, s14, 31
	s_lshl_b64 s[16:17], s[14:15], 19
	s_add_u32 s16, s36, s16
	s_addc_u32 s17, s37, s17
	s_and_b64 s[18:19], s[8:9], exec
	s_cselect_b32 s15, s17, s25
	s_cselect_b32 s29, s16, s24
	s_ashr_i32 s13, s12, 31
	s_lshl_b64 s[18:19], s[12:13], 19
	s_add_u32 s18, s26, s18
	s_addc_u32 s19, s56, s19
	s_and_b64 s[22:23], s[8:9], exec
	s_cselect_b32 s13, s19, s1
	s_cselect_b32 s22, s18, s0
	s_add_u32 s24, s24, 0x40080
	s_addc_u32 s25, s25, 0
	s_add_u32 s23, s0, 0x100
	v_mov_b32_e32 v20, 0
	s_addc_u32 s35, s1, 0
	s_mov_b32 s60, -2
	v_mov_b32_e32 v21, v20
	v_mov_b32_e32 v22, v20
	v_mov_b32_e32 v23, v20
	v_mov_b32_e32 v24, v20
	v_mov_b32_e32 v25, v20
	v_mov_b32_e32 v26, v20
	v_mov_b32_e32 v27, v20
	v_mov_b32_e32 v36, v20
	v_mov_b32_e32 v37, v20
	v_mov_b32_e32 v38, v20
	v_mov_b32_e32 v39, v20
	v_mov_b32_e32 v40, v20
	v_mov_b32_e32 v41, v20
	v_mov_b32_e32 v42, v20
	v_mov_b32_e32 v43, v20
	v_mov_b32_e32 v52, v20
	v_mov_b32_e32 v53, v20
	v_mov_b32_e32 v54, v20
	v_mov_b32_e32 v55, v20
	v_mov_b32_e32 v56, v20
	v_mov_b32_e32 v57, v20
	v_mov_b32_e32 v58, v20
	v_mov_b32_e32 v59, v20
	v_mov_b32_e32 v68, v20
	v_mov_b32_e32 v69, v20
	v_mov_b32_e32 v70, v20
	v_mov_b32_e32 v71, v20
	v_mov_b32_e32 v72, v20
	v_mov_b32_e32 v73, v20
	v_mov_b32_e32 v74, v20
	v_mov_b32_e32 v75, v20
	v_mov_b32_e32 v28, v20
	v_mov_b32_e32 v29, v20
	v_mov_b32_e32 v30, v20
	v_mov_b32_e32 v31, v20
	v_mov_b32_e32 v32, v20
	v_mov_b32_e32 v33, v20
	v_mov_b32_e32 v34, v20
	v_mov_b32_e32 v35, v20
	v_mov_b32_e32 v44, v20
	v_mov_b32_e32 v45, v20
	v_mov_b32_e32 v46, v20
	v_mov_b32_e32 v47, v20
	v_mov_b32_e32 v48, v20
	v_mov_b32_e32 v49, v20
	v_mov_b32_e32 v50, v20
	v_mov_b32_e32 v51, v20
	v_mov_b32_e32 v60, v20
	v_mov_b32_e32 v61, v20
	v_mov_b32_e32 v62, v20
	v_mov_b32_e32 v63, v20
	v_mov_b32_e32 v64, v20
	v_mov_b32_e32 v65, v20
	v_mov_b32_e32 v66, v20
	v_mov_b32_e32 v67, v20
	v_mov_b32_e32 v76, v20
	v_mov_b32_e32 v77, v20
	v_mov_b32_e32 v78, v20
	v_mov_b32_e32 v79, v20
	v_mov_b32_e32 v80, v20
	v_mov_b32_e32 v81, v20
	v_mov_b32_e32 v82, v20
	v_mov_b32_e32 v83, v20
	v_mov_b32_e32 v84, v20
	v_mov_b32_e32 v85, v20
	v_mov_b32_e32 v86, v20
	v_mov_b32_e32 v87, v20
	v_mov_b32_e32 v88, v20
	v_mov_b32_e32 v89, v20
	v_mov_b32_e32 v90, v20
	v_mov_b32_e32 v91, v20
	v_mov_b32_e32 v100, v20
	v_mov_b32_e32 v101, v20
	v_mov_b32_e32 v102, v20
	v_mov_b32_e32 v103, v20
	v_mov_b32_e32 v104, v20
	v_mov_b32_e32 v105, v20
	v_mov_b32_e32 v106, v20
	v_mov_b32_e32 v107, v20
	v_mov_b32_e32 v116, v20
	v_mov_b32_e32 v117, v20
	v_mov_b32_e32 v118, v20
	v_mov_b32_e32 v119, v20
	v_mov_b32_e32 v120, v20
	v_mov_b32_e32 v121, v20
	v_mov_b32_e32 v122, v20
	v_mov_b32_e32 v123, v20
	v_mov_b32_e32 v132, v20
	v_mov_b32_e32 v133, v20
	v_mov_b32_e32 v134, v20
	v_mov_b32_e32 v135, v20
	v_mov_b32_e32 v136, v20
	v_mov_b32_e32 v137, v20
	v_mov_b32_e32 v138, v20
	v_mov_b32_e32 v139, v20
	v_mov_b32_e32 v92, v20
	v_mov_b32_e32 v93, v20
	v_mov_b32_e32 v94, v20
	v_mov_b32_e32 v95, v20
	v_mov_b32_e32 v96, v20
	v_mov_b32_e32 v97, v20
	v_mov_b32_e32 v98, v20
	v_mov_b32_e32 v99, v20
	v_mov_b32_e32 v108, v20
	v_mov_b32_e32 v109, v20
	v_mov_b32_e32 v110, v20
	v_mov_b32_e32 v111, v20
	v_mov_b32_e32 v112, v20
	v_mov_b32_e32 v113, v20
	v_mov_b32_e32 v114, v20
	v_mov_b32_e32 v115, v20
	v_mov_b32_e32 v124, v20
	v_mov_b32_e32 v125, v20
	v_mov_b32_e32 v126, v20
	v_mov_b32_e32 v127, v20
	v_mov_b32_e32 v128, v20
	v_mov_b32_e32 v129, v20
	v_mov_b32_e32 v130, v20
	v_mov_b32_e32 v131, v20
	v_mov_b32_e32 v140, v20
	v_mov_b32_e32 v141, v20
	v_mov_b32_e32 v142, v20
	v_mov_b32_e32 v143, v20
	v_mov_b32_e32 v144, v20
	v_mov_b32_e32 v145, v20
	v_mov_b32_e32 v146, v20
	v_mov_b32_e32 v147, v20

; template <class Epi, class Sched, bool ALIGN_EPI = false, bool SP2 = false>
; __device__ __forceinline__ void gemm_phase(PG8_LAS unsigned char* lds, const Gemm g, const Sched& S, const Epi& E) {
;     ...
;         const bool has_next = S.next(ui + 1, nxt);
;         const char* nA = has_next ? (const char*)g.A + (size_t)nxt.pm * tstep : cA; const char* nB = has_next ? (const char*)g.Bt + (size_t)nxt.pn * tstep : cB;
;         for (int t = 0; t < nt; t += 2) {
;             const bool last = (t == nt - 2);
;             const char* a1 = cA + (size_t)(t + 1) * kstep;
;             const char* a2 = last ? nA : cA + (size_t)(t + 2) * kstep; const char* b2 = last ? nB : cB + (size_t)(t + 2) * kstep;
;     ...
; #pragma unroll
;         for (int a = 0; a < 2; ++a)
; #pragma unroll
;             for (int b = 0; b < 2; ++b)
; #pragma unroll
;                 for (int m = 0; m < 4; ++m)
; #pragma unroll
;                     for (int n = 0; n < 2; ++n) acc[a][b][m][n] = (f32x4){0.f, 0.f, 0.f, 0.f};
;         cur = nxt; cA = nA; cB = nB; ++ui;
.LBB0_941:
	s_ashr_i32 s59, s58, 31
	s_lshl_b64 s[6:7], s[58:59], 21
	s_add_u32 s6, s48, s6
	s_addc_u32 s7, s49, s7
	s_and_b64 s[12:13], s[8:9], exec
	s_cselect_b32 s59, s7, s11
	s_cselect_b32 s62, s6, s10
	s_ashr_i32 s57, s56, 31
	s_lshl_b64 s[12:13], s[56:57], 21
	s_add_u32 s24, s26, s12
	s_addc_u32 s25, s66, s13
	s_and_b64 s[12:13], s[8:9], exec
	s_cselect_b32 s57, s25, s1
	s_cselect_b32 s22, s24, s0
	s_add_u32 s10, s10, 0x100080
	s_addc_u32 s11, s11, 0
	s_add_u32 s23, s0, 0x100
	v_mov_b32_e32 v20, 0
	s_addc_u32 s35, s1, 0
	s_mov_b32 s60, -2
	v_mov_b32_e32 v21, v20
	v_mov_b32_e32 v22, v20
	v_mov_b32_e32 v23, v20
	v_mov_b32_e32 v24, v20
	s_waitcnt lgkmcnt(0)
	v_mov_b32_e32 v25, v20
	v_mov_b32_e32 v26, v20
	v_mov_b32_e32 v27, v20
	v_mov_b32_e32 v36, v20
	v_mov_b32_e32 v37, v20
	v_mov_b32_e32 v38, v20
	v_mov_b32_e32 v39, v20
	v_mov_b32_e32 v40, v20
	v_mov_b32_e32 v41, v20
	v_mov_b32_e32 v42, v20
	v_mov_b32_e32 v43, v20
	v_mov_b32_e32 v52, v20
	v_mov_b32_e32 v53, v20
	v_mov_b32_e32 v54, v20
	v_mov_b32_e32 v55, v20
	v_mov_b32_e32 v56, v20
	v_mov_b32_e32 v57, v20
	v_mov_b32_e32 v58, v20
	v_mov_b32_e32 v59, v20
	v_mov_b32_e32 v68, v20
	v_mov_b32_e32 v69, v20
	v_mov_b32_e32 v70, v20
	v_mov_b32_e32 v71, v20
	v_mov_b32_e32 v72, v20
	v_mov_b32_e32 v73, v20
	v_mov_b32_e32 v74, v20
	v_mov_b32_e32 v75, v20
	v_mov_b32_e32 v28, v20
	v_mov_b32_e32 v29, v20
	v_mov_b32_e32 v30, v20
	v_mov_b32_e32 v31, v20
	v_mov_b32_e32 v32, v20
	v_mov_b32_e32 v33, v20
	v_mov_b32_e32 v34, v20
	v_mov_b32_e32 v35, v20
	v_mov_b32_e32 v44, v20
	v_mov_b32_e32 v45, v20
	v_mov_b32_e32 v46, v20
	v_mov_b32_e32 v47, v20
	v_mov_b32_e32 v48, v20
	v_mov_b32_e32 v49, v20
	v_mov_b32_e32 v50, v20
	v_mov_b32_e32 v51, v20
	v_mov_b32_e32 v60, v20
	v_mov_b32_e32 v61, v20
	v_mov_b32_e32 v62, v20
	v_mov_b32_e32 v63, v20
	v_mov_b32_e32 v64, v20
	v_mov_b32_e32 v65, v20
	v_mov_b32_e32 v66, v20
	v_mov_b32_e32 v67, v20
	v_mov_b32_e32 v76, v20
	v_mov_b32_e32 v77, v20
	v_mov_b32_e32 v78, v20
	v_mov_b32_e32 v79, v20
	v_mov_b32_e32 v80, v20
	v_mov_b32_e32 v81, v20
	v_mov_b32_e32 v82, v20
	v_mov_b32_e32 v83, v20
	v_mov_b32_e32 v84, v20
	v_mov_b32_e32 v85, v20
	v_mov_b32_e32 v86, v20
	v_mov_b32_e32 v87, v20
	v_mov_b32_e32 v88, v20
	v_mov_b32_e32 v89, v20
	v_mov_b32_e32 v90, v20
	v_mov_b32_e32 v91, v20
	v_mov_b32_e32 v100, v20
	v_mov_b32_e32 v101, v20
	v_mov_b32_e32 v102, v20
	v_mov_b32_e32 v103, v20
	v_mov_b32_e32 v104, v20
	v_mov_b32_e32 v105, v20
	v_mov_b32_e32 v106, v20
	v_mov_b32_e32 v107, v20
	v_mov_b32_e32 v116, v20
	v_mov_b32_e32 v117, v20
	v_mov_b32_e32 v118, v20
	v_mov_b32_e32 v119, v20
	v_mov_b32_e32 v120, v20
	v_mov_b32_e32 v121, v20
	v_mov_b32_e32 v122, v20
	v_mov_b32_e32 v123, v20
	v_mov_b32_e32 v132, v20
	v_mov_b32_e32 v133, v20
	v_mov_b32_e32 v134, v20
	v_mov_b32_e32 v135, v20
	v_mov_b32_e32 v136, v20
	v_mov_b32_e32 v137, v20
	v_mov_b32_e32 v138, v20
	v_mov_b32_e32 v139, v20
	v_mov_b32_e32 v92, v20
	v_mov_b32_e32 v93, v20
	v_mov_b32_e32 v94, v20
	v_mov_b32_e32 v95, v20
	v_mov_b32_e32 v96, v20
	v_mov_b32_e32 v97, v20
	v_mov_b32_e32 v98, v20
	v_mov_b32_e32 v99, v20
	v_mov_b32_e32 v108, v20
	v_mov_b32_e32 v109, v20
	v_mov_b32_e32 v110, v20
	v_mov_b32_e32 v111, v20
	v_mov_b32_e32 v112, v20
	v_mov_b32_e32 v113, v20
	v_mov_b32_e32 v114, v20
	v_mov_b32_e32 v115, v20
	v_mov_b32_e32 v124, v20
	v_mov_b32_e32 v125, v20
	v_mov_b32_e32 v126, v20
	v_mov_b32_e32 v127, v20
	v_mov_b32_e32 v128, v20
	v_mov_b32_e32 v129, v20
	v_mov_b32_e32 v130, v20
	v_mov_b32_e32 v131, v20
	v_mov_b32_e32 v140, v20
	v_mov_b32_e32 v141, v20
	v_mov_b32_e32 v142, v20
	v_mov_b32_e32 v143, v20
	v_mov_b32_e32 v144, v20
	v_mov_b32_e32 v145, v20
	v_mov_b32_e32 v146, v20
	v_mov_b32_e32 v147, v20
